# P3 epilogue rewritten by hand: residual loads software-pipelined (5 row groups in flight), scalar bases with saddr addressing, one 64-lane rss atomic per 64-row strip (2 instead of 8 per wave and tile
# baseline (speedup 1.0000x reference)
;     __device__ __forceinline__ void operator()(f32x4 (&acc)[2][2][4][2], const Unit& u, int wr, int wc, int fr, int fq) const {
;     ...
;         const int col0 = u.pn * 256 + wc * 32 + 8 * fq;
;     ...
; #pragma unroll
;         for (int ai = 0; ai < 2; ++ai) {
;             RES1_LD(0) RES1_LD(1) RES1_LD(2) RES1_LD(3)
;             RES1_DO(0) RES1_DO(1) RES1_DO(2) RES1_DO(3)
;             asm volatile("" ::: "memory");
.LBB0_472:
	s_lshl_b32 s0, s0, 8
	s_add_i32 s0, s0, s41
	s_lshl_b32 s1, s2, 8
	s_or_b32 s1, s1, s42
	s_cmp_lt_i32 s0, s40
	s_cselect_b32 s26, s36, s38
	s_cselect_b32 s27, s37, s39
	s_cselect_b32 s2, 0, s40
	s_sub_i32 s2, s0, s2
	s_lshl_b32 s2, s2, 12
	s_lshl_b32 s15, s1, 2
	s_add_i32 s2, s2, s15
	s_add_u32 s26, s26, s2
	s_addc_u32 s27, s27, 0
	v_lshlrev_b32_e32 v228, 12, v204
	v_lshl_or_b32 v228, v205, 5, v228
	s_lshl_b32 s2, s0, 11
	s_lshl_b32 s15, s1, 1
	s_add_i32 s2, s2, s15
	s_add_u32 s28, s62, s2
	s_addc_u32 s29, s63, 0
	s_lshl_b32 s2, s0, 2
	s_add_u32 s6, s60, s2
	s_addc_u32 s7, s61, 0
	global_load_dwordx4 v[128:131], v228, s[26:27]
	global_load_dwordx4 v[132:135], v228, s[26:27] offset:16
	global_load_dwordx4 v[136:139], v228, s[26:27] offset:512
	global_load_dwordx4 v[140:143], v228, s[26:27] offset:528
	s_add_u32 s26, s26, 0x10000
	s_addc_u32 s27, s27, 0
	global_load_dwordx4 v[144:147], v228, s[26:27]
	global_load_dwordx4 v[148:151], v228, s[26:27] offset:16
	global_load_dwordx4 v[152:155], v228, s[26:27] offset:512
	global_load_dwordx4 v[156:159], v228, s[26:27] offset:528
	s_add_u32 s26, s26, 0x10000
	s_addc_u32 s27, s27, 0
	global_load_dwordx4 v[160:163], v228, s[26:27]
	global_load_dwordx4 v[164:167], v228, s[26:27] offset:16
	global_load_dwordx4 v[168:171], v228, s[26:27] offset:512
	global_load_dwordx4 v[172:175], v228, s[26:27] offset:528
	s_add_u32 s26, s26, 0x10000
	s_addc_u32 s27, s27, 0
	global_load_dwordx4 v[212:215], v228, s[26:27]
	global_load_dwordx4 v[216:219], v228, s[26:27] offset:16
	global_load_dwordx4 v[220:223], v228, s[26:27] offset:512
	global_load_dwordx4 v[224:227], v228, s[26:27] offset:528
	s_add_u32 s26, s26, 0x50000
	s_addc_u32 s27, s27, 0
	global_load_dwordx4 v[232:235], v228, s[26:27]
	global_load_dwordx4 v[236:239], v228, s[26:27] offset:16
	global_load_dwordx4 v[240:243], v228, s[26:27] offset:512
	global_load_dwordx4 v[244:247], v228, s[26:27] offset:528
	v_lshlrev_b32_e32 v229, 11, v204
	v_lshl_or_b32 v229, v205, 4, v229
	v_lshlrev_b32_e32 v230, 2, v210
	v_xor_b32_e32 v231, 64, v230
	v_xor_b32_e32 v252, 0x80, v230
	v_and_b32_e32 v253, 1, v205
	v_cmp_ne_u32_e64 s[50:51], 0, v253
	v_and_b32_e32 v253, 2, v205
	v_cmp_ne_u32_e64 s[52:53], 0, v253
	s_waitcnt vmcnt(16)
	v_pk_add_f32 v[124:125], v[124:125], v[128:129]
	v_pk_add_f32 v[126:127], v[126:127], v[130:131]
	v_pk_add_f32 v[120:121], v[120:121], v[132:133]
	v_pk_add_f32 v[122:123], v[122:123], v[134:135]
	v_pk_add_f32 v[116:117], v[116:117], v[136:137]
	v_pk_add_f32 v[118:119], v[118:119], v[138:139]
	v_pk_add_f32 v[112:113], v[112:113], v[140:141]
	v_pk_add_f32 v[114:115], v[114:115], v[142:143]
	v_pk_mul_f32 v[128:129], v[124:125], v[124:125]
	v_pk_mul_f32 v[130:131], v[126:127], v[126:127]
	v_pk_fma_f32 v[128:129], v[120:121], v[120:121], v[128:129]
	v_pk_fma_f32 v[130:131], v[122:123], v[122:123], v[130:131]
	v_pk_fma_f32 v[128:129], v[116:117], v[116:117], v[128:129]
	v_pk_fma_f32 v[130:131], v[118:119], v[118:119], v[130:131]
	v_pk_fma_f32 v[128:129], v[112:113], v[112:113], v[128:129]
	v_pk_fma_f32 v[130:131], v[114:115], v[114:115], v[130:131]
	v_cvt_pk_bf16_f32 v132, v124, v125
	v_cvt_pk_bf16_f32 v133, v126, v127
	v_cvt_pk_bf16_f32 v134, v120, v121
	v_cvt_pk_bf16_f32 v135, v122, v123
	v_add_f32_e32 v128, v128, v129
	v_cvt_pk_bf16_f32 v136, v116, v117
	v_cvt_pk_bf16_f32 v137, v118, v119
	v_add_f32_e32 v130, v130, v131
	v_cvt_pk_bf16_f32 v138, v112, v113
	v_cvt_pk_bf16_f32 v139, v114, v115
	v_add_f32_e32 v192, v128, v130
	global_store_dwordx4 v229, v[132:135], s[28:29]
	global_store_dwordx4 v229, v[136:139], s[28:29] offset:256
	s_add_u32 s26, s26, 0x10000
	s_addc_u32 s27, s27, 0
	global_load_dwordx4 v[128:131], v228, s[26:27]
	global_load_dwordx4 v[132:135], v228, s[26:27] offset:16
	global_load_dwordx4 v[136:139], v228, s[26:27] offset:512
	global_load_dwordx4 v[140:143], v228, s[26:27] offset:528
	s_waitcnt vmcnt(18)
	v_pk_add_f32 v[108:109], v[108:109], v[144:145]
	v_pk_add_f32 v[110:111], v[110:111], v[146:147]
	v_pk_add_f32 v[104:105], v[104:105], v[148:149]
	v_pk_add_f32 v[106:107], v[106:107], v[150:151]
	v_pk_add_f32 v[100:101], v[100:101], v[152:153]
	v_pk_add_f32 v[102:103], v[102:103], v[154:155]
	v_pk_add_f32 v[96:97], v[96:97], v[156:157]
	v_pk_add_f32 v[98:99], v[98:99], v[158:159]
	v_pk_mul_f32 v[144:145], v[108:109], v[108:109]
	v_pk_mul_f32 v[146:147], v[110:111], v[110:111]
	v_pk_fma_f32 v[144:145], v[104:105], v[104:105], v[144:145]
	v_pk_fma_f32 v[146:147], v[106:107], v[106:107], v[146:147]
	v_pk_fma_f32 v[144:145], v[100:101], v[100:101], v[144:145]
	v_pk_fma_f32 v[146:147], v[102:103], v[102:103], v[146:147]
	v_pk_fma_f32 v[144:145], v[96:97], v[96:97], v[144:145]
	v_pk_fma_f32 v[146:147], v[98:99], v[98:99], v[146:147]
	v_cvt_pk_bf16_f32 v148, v108, v109
	v_cvt_pk_bf16_f32 v149, v110, v111
	v_cvt_pk_bf16_f32 v150, v104, v105
	v_cvt_pk_bf16_f32 v151, v106, v107
	v_add_f32_e32 v144, v144, v145
	v_cvt_pk_bf16_f32 v152, v100, v101
	v_cvt_pk_bf16_f32 v153, v102, v103
	v_add_f32_e32 v146, v146, v147
	v_cvt_pk_bf16_f32 v154, v96, v97
	v_cvt_pk_bf16_f32 v155, v98, v99
	v_add_f32_e32 v193, v144, v146
	s_add_u32 s28, s28, 0x8000
	s_addc_u32 s29, s29, 0
	global_store_dwordx4 v229, v[148:151], s[28:29]
	global_store_dwordx4 v229, v[152:155], s[28:29] offset:256
	s_add_u32 s26, s26, 0x10000
	s_addc_u32 s27, s27, 0
	global_load_dwordx4 v[144:147], v228, s[26:27]
	global_load_dwordx4 v[148:151], v228, s[26:27] offset:16
	global_load_dwordx4 v[152:155], v228, s[26:27] offset:512
	global_load_dwordx4 v[156:159], v228, s[26:27] offset:528
	s_waitcnt vmcnt(20)
	v_pk_add_f32 v[92:93], v[92:93], v[160:161]
	v_pk_add_f32 v[94:95], v[94:95], v[162:163]
	v_pk_add_f32 v[88:89], v[88:89], v[164:165]
	v_pk_add_f32 v[90:91], v[90:91], v[166:167]
	v_pk_add_f32 v[84:85], v[84:85], v[168:169]
	v_pk_add_f32 v[86:87], v[86:87], v[170:171]
	v_pk_add_f32 v[80:81], v[80:81], v[172:173]
	v_pk_add_f32 v[82:83], v[82:83], v[174:175]
	v_pk_mul_f32 v[160:161], v[92:93], v[92:93]
	v_pk_mul_f32 v[162:163], v[94:95], v[94:95]
	v_pk_fma_f32 v[160:161], v[88:89], v[88:89], v[160:161]
	v_pk_fma_f32 v[162:163], v[90:91], v[90:91], v[162:163]
	v_pk_fma_f32 v[160:161], v[84:85], v[84:85], v[160:161]
	v_pk_fma_f32 v[162:163], v[86:87], v[86:87], v[162:163]
	v_pk_fma_f32 v[160:161], v[80:81], v[80:81], v[160:161]
	v_pk_fma_f32 v[162:163], v[82:83], v[82:83], v[162:163]
	v_cvt_pk_bf16_f32 v164, v92, v93
	v_cvt_pk_bf16_f32 v165, v94, v95
	v_cvt_pk_bf16_f32 v166, v88, v89
	v_cvt_pk_bf16_f32 v167, v90, v91
	v_add_f32_e32 v160, v160, v161
	v_cvt_pk_bf16_f32 v168, v84, v85
	v_cvt_pk_bf16_f32 v169, v86, v87
	v_add_f32_e32 v162, v162, v163
	v_cvt_pk_bf16_f32 v170, v80, v81
	v_cvt_pk_bf16_f32 v171, v82, v83
	v_add_f32_e32 v194, v160, v162
	s_add_u32 s28, s28, 0x8000
	s_addc_u32 s29, s29, 0
	global_store_dwordx4 v229, v[164:167], s[28:29]
	global_store_dwordx4 v229, v[168:171], s[28:29] offset:256
	s_add_u32 s26, s26, 0x10000
	s_addc_u32 s27, s27, 0
	global_load_dwordx4 v[160:163], v228, s[26:27]
	global_load_dwordx4 v[164:167], v228, s[26:27] offset:16
	global_load_dwordx4 v[168:171], v228, s[26:27] offset:512
	global_load_dwordx4 v[172:175], v228, s[26:27] offset:528
	s_waitcnt vmcnt(22)
	v_pk_add_f32 v[76:77], v[76:77], v[212:213]
	v_pk_add_f32 v[78:79], v[78:79], v[214:215]
	v_pk_add_f32 v[72:73], v[72:73], v[216:217]
	v_pk_add_f32 v[74:75], v[74:75], v[218:219]
	v_pk_add_f32 v[68:69], v[68:69], v[220:221]
	v_pk_add_f32 v[70:71], v[70:71], v[222:223]
	v_pk_add_f32 v[64:65], v[64:65], v[224:225]
	v_pk_add_f32 v[66:67], v[66:67], v[226:227]
	v_pk_mul_f32 v[212:213], v[76:77], v[76:77]
	v_pk_mul_f32 v[214:215], v[78:79], v[78:79]
	v_pk_fma_f32 v[212:213], v[72:73], v[72:73], v[212:213]
	v_pk_fma_f32 v[214:215], v[74:75], v[74:75], v[214:215]
	v_pk_fma_f32 v[212:213], v[68:69], v[68:69], v[212:213]
	v_pk_fma_f32 v[214:215], v[70:71], v[70:71], v[214:215]
	v_pk_fma_f32 v[212:213], v[64:65], v[64:65], v[212:213]
	v_pk_fma_f32 v[214:215], v[66:67], v[66:67], v[214:215]
	v_cvt_pk_bf16_f32 v216, v76, v77
	v_cvt_pk_bf16_f32 v217, v78, v79
	v_cvt_pk_bf16_f32 v218, v72, v73
	v_cvt_pk_bf16_f32 v219, v74, v75
	v_add_f32_e32 v212, v212, v213
	v_cvt_pk_bf16_f32 v220, v68, v69
	v_cvt_pk_bf16_f32 v221, v70, v71
	v_add_f32_e32 v214, v214, v215
	v_cvt_pk_bf16_f32 v222, v64, v65
	v_cvt_pk_bf16_f32 v223, v66, v67
	v_add_f32_e32 v195, v212, v214
	s_add_u32 s28, s28, 0x8000
	s_addc_u32 s29, s29, 0
	global_store_dwordx4 v229, v[216:219], s[28:29]
	global_store_dwordx4 v229, v[220:223], s[28:29] offset:256
	v_cndmask_b32_e64 v196, v192, v193, s[50:51]
	v_cndmask_b32_e64 v197, v193, v192, s[50:51]
	v_cndmask_b32_e64 v198, v194, v195, s[50:51]
	v_cndmask_b32_e64 v199, v195, v194, s[50:51]
	ds_bpermute_b32 v200, v231, v197
	ds_bpermute_b32 v201, v231, v199
	s_waitcnt lgkmcnt(0)
	v_add_f32_e32 v196, v196, v200
	v_add_f32_e32 v198, v198, v201
	v_cndmask_b32_e64 v202, v196, v198, s[52:53]
	v_cndmask_b32_e64 v203, v198, v196, s[52:53]
	ds_bpermute_b32 v248, v252, v203
	s_waitcnt lgkmcnt(0)
	v_add_f32_e32 v249, v202, v248
	global_atomic_add_f32 v230, v249, s[6:7]
	s_waitcnt vmcnt(21)
	v_pk_add_f32 v[60:61], v[60:61], v[232:233]
	v_pk_add_f32 v[62:63], v[62:63], v[234:235]
	v_pk_add_f32 v[56:57], v[56:57], v[236:237]
	v_pk_add_f32 v[58:59], v[58:59], v[238:239]
	v_pk_add_f32 v[52:53], v[52:53], v[240:241]
	v_pk_add_f32 v[54:55], v[54:55], v[242:243]
	v_pk_add_f32 v[48:49], v[48:49], v[244:245]
	v_pk_add_f32 v[50:51], v[50:51], v[246:247]
	v_pk_mul_f32 v[232:233], v[60:61], v[60:61]
	v_pk_mul_f32 v[234:235], v[62:63], v[62:63]
	v_pk_fma_f32 v[232:233], v[56:57], v[56:57], v[232:233]
	v_pk_fma_f32 v[234:235], v[58:59], v[58:59], v[234:235]
	v_pk_fma_f32 v[232:233], v[52:53], v[52:53], v[232:233]
	v_pk_fma_f32 v[234:235], v[54:55], v[54:55], v[234:235]
	v_pk_fma_f32 v[232:233], v[48:49], v[48:49], v[232:233]
	v_pk_fma_f32 v[234:235], v[50:51], v[50:51], v[234:235]
	v_cvt_pk_bf16_f32 v236, v60, v61
	v_cvt_pk_bf16_f32 v237, v62, v63
	v_cvt_pk_bf16_f32 v238, v56, v57
	v_cvt_pk_bf16_f32 v239, v58, v59
	v_add_f32_e32 v232, v232, v233
	v_cvt_pk_bf16_f32 v240, v52, v53
	v_cvt_pk_bf16_f32 v241, v54, v55
	v_add_f32_e32 v234, v234, v235
	v_cvt_pk_bf16_f32 v242, v48, v49
	v_cvt_pk_bf16_f32 v243, v50, v51
	v_add_f32_e32 v192, v232, v234
	s_add_u32 s28, s28, 0x28000
	s_addc_u32 s29, s29, 0
	global_store_dwordx4 v229, v[236:239], s[28:29]
	global_store_dwordx4 v229, v[240:243], s[28:29] offset:256
	s_waitcnt vmcnt(17)
;     __device__ __forceinline__ void operator()(f32x4 (&acc)[2][2][4][2], const Unit& u, int wr, int wc, int fr, int fq) const {
;     ...
; #pragma unroll
;         for (int ai = 0; ai < 2; ++ai) {
;             RES1_LD(0) RES1_LD(1) RES1_LD(2) RES1_LD(3)
;             RES1_DO(0) RES1_DO(1) RES1_DO(2) RES1_DO(3)
	v_pk_add_f32 v[44:45], v[44:45], v[128:129]
	v_pk_add_f32 v[46:47], v[46:47], v[130:131]
	v_pk_add_f32 v[40:41], v[40:41], v[132:133]
	v_pk_add_f32 v[42:43], v[42:43], v[134:135]
	v_pk_add_f32 v[36:37], v[36:37], v[136:137]
	v_pk_add_f32 v[38:39], v[38:39], v[138:139]
	v_pk_add_f32 v[32:33], v[32:33], v[140:141]
	v_pk_add_f32 v[34:35], v[34:35], v[142:143]
	v_pk_mul_f32 v[128:129], v[44:45], v[44:45]
	v_pk_mul_f32 v[130:131], v[46:47], v[46:47]
	v_pk_fma_f32 v[128:129], v[40:41], v[40:41], v[128:129]
	v_pk_fma_f32 v[130:131], v[42:43], v[42:43], v[130:131]
	v_pk_fma_f32 v[128:129], v[36:37], v[36:37], v[128:129]
	v_pk_fma_f32 v[130:131], v[38:39], v[38:39], v[130:131]
	v_pk_fma_f32 v[128:129], v[32:33], v[32:33], v[128:129]
	v_pk_fma_f32 v[130:131], v[34:35], v[34:35], v[130:131]
	v_cvt_pk_bf16_f32 v132, v44, v45
	v_cvt_pk_bf16_f32 v133, v46, v47
	v_cvt_pk_bf16_f32 v134, v40, v41
	v_cvt_pk_bf16_f32 v135, v42, v43
	v_add_f32_e32 v128, v128, v129
	v_cvt_pk_bf16_f32 v136, v36, v37
	v_cvt_pk_bf16_f32 v137, v38, v39
	v_add_f32_e32 v130, v130, v131
	v_cvt_pk_bf16_f32 v138, v32, v33
	v_cvt_pk_bf16_f32 v139, v34, v35
	v_add_f32_e32 v193, v128, v130
	s_add_u32 s28, s28, 0x8000
	s_addc_u32 s29, s29, 0
	global_store_dwordx4 v229, v[132:135], s[28:29]
	global_store_dwordx4 v229, v[136:139], s[28:29] offset:256
	s_waitcnt vmcnt(13)
	v_pk_add_f32 v[28:29], v[28:29], v[144:145]
	v_pk_add_f32 v[30:31], v[30:31], v[146:147]
	v_pk_add_f32 v[24:25], v[24:25], v[148:149]
	v_pk_add_f32 v[26:27], v[26:27], v[150:151]
	v_pk_add_f32 v[20:21], v[20:21], v[152:153]
	v_pk_add_f32 v[22:23], v[22:23], v[154:155]
	v_pk_add_f32 v[16:17], v[16:17], v[156:157]
	v_pk_add_f32 v[18:19], v[18:19], v[158:159]
	v_pk_mul_f32 v[144:145], v[28:29], v[28:29]
	v_pk_mul_f32 v[146:147], v[30:31], v[30:31]
	v_pk_fma_f32 v[144:145], v[24:25], v[24:25], v[144:145]
	v_pk_fma_f32 v[146:147], v[26:27], v[26:27], v[146:147]
	v_pk_fma_f32 v[144:145], v[20:21], v[20:21], v[144:145]
	v_pk_fma_f32 v[146:147], v[22:23], v[22:23], v[146:147]
	v_pk_fma_f32 v[144:145], v[16:17], v[16:17], v[144:145]
	v_pk_fma_f32 v[146:147], v[18:19], v[18:19], v[146:147]
	v_cvt_pk_bf16_f32 v148, v28, v29
	v_cvt_pk_bf16_f32 v149, v30, v31
	v_cvt_pk_bf16_f32 v150, v24, v25
	v_cvt_pk_bf16_f32 v151, v26, v27
	v_add_f32_e32 v144, v144, v145
	v_cvt_pk_bf16_f32 v152, v20, v21
	v_cvt_pk_bf16_f32 v153, v22, v23
	v_add_f32_e32 v146, v146, v147
	v_cvt_pk_bf16_f32 v154, v16, v17
	v_cvt_pk_bf16_f32 v155, v18, v19
	v_add_f32_e32 v194, v144, v146
	s_add_u32 s28, s28, 0x8000
	s_addc_u32 s29, s29, 0
	global_store_dwordx4 v229, v[148:151], s[28:29]
	global_store_dwordx4 v229, v[152:155], s[28:29] offset:256
	s_waitcnt vmcnt(9)
	v_pk_add_f32 v[12:13], v[12:13], v[160:161]
	v_pk_add_f32 v[14:15], v[14:15], v[162:163]
	v_pk_add_f32 v[8:9], v[8:9], v[164:165]
	v_pk_add_f32 v[10:11], v[10:11], v[166:167]
	v_pk_add_f32 v[4:5], v[4:5], v[168:169]
	v_pk_add_f32 v[6:7], v[6:7], v[170:171]
	v_pk_add_f32 v[0:1], v[0:1], v[172:173]
	v_pk_add_f32 v[2:3], v[2:3], v[174:175]
	v_pk_mul_f32 v[160:161], v[12:13], v[12:13]
	v_pk_mul_f32 v[162:163], v[14:15], v[14:15]
	v_pk_fma_f32 v[160:161], v[8:9], v[8:9], v[160:161]
	v_pk_fma_f32 v[162:163], v[10:11], v[10:11], v[162:163]
	v_pk_fma_f32 v[160:161], v[4:5], v[4:5], v[160:161]
	v_pk_fma_f32 v[162:163], v[6:7], v[6:7], v[162:163]
	v_pk_fma_f32 v[160:161], v[0:1], v[0:1], v[160:161]
	v_pk_fma_f32 v[162:163], v[2:3], v[2:3], v[162:163]
	v_cvt_pk_bf16_f32 v164, v12, v13
	v_cvt_pk_bf16_f32 v165, v14, v15
	v_cvt_pk_bf16_f32 v166, v8, v9
	v_cvt_pk_bf16_f32 v167, v10, v11
	v_add_f32_e32 v160, v160, v161
	v_cvt_pk_bf16_f32 v168, v4, v5
	v_cvt_pk_bf16_f32 v169, v6, v7
	v_add_f32_e32 v162, v162, v163
	v_cvt_pk_bf16_f32 v170, v0, v1
	v_cvt_pk_bf16_f32 v171, v2, v3
	v_add_f32_e32 v195, v160, v162
	s_add_u32 s28, s28, 0x8000
	s_addc_u32 s29, s29, 0
	global_store_dwordx4 v229, v[164:167], s[28:29]
	global_store_dwordx4 v229, v[168:171], s[28:29] offset:256
	v_cndmask_b32_e64 v196, v192, v193, s[50:51]
	v_cndmask_b32_e64 v197, v193, v192, s[50:51]
	v_cndmask_b32_e64 v198, v194, v195, s[50:51]
	v_cndmask_b32_e64 v199, v195, v194, s[50:51]
	ds_bpermute_b32 v200, v231, v197
	ds_bpermute_b32 v201, v231, v199
	s_waitcnt lgkmcnt(0)
	v_add_f32_e32 v196, v196, v200
	v_add_f32_e32 v198, v198, v201
	v_cndmask_b32_e64 v202, v196, v198, s[52:53]
	v_cndmask_b32_e64 v203, v198, v196, s[52:53]
	ds_bpermute_b32 v248, v252, v203
	s_waitcnt lgkmcnt(0)
	v_add_f32_e32 v249, v202, v248
	global_atomic_add_f32 v230, v249, s[6:7] offset:512
	s_andn2_b64 vcc, exec, s[4:5]
	s_mov_b64 s[0:1], -1
	s_cbranch_vccnz .LBB0_461
	s_andn2_b64 vcc, exec, s[8:9]
	s_cbranch_vccnz .LBB0_460
	s_barrier
	s_branch .LBB0_460
